# k7
# speedup vs baseline: 1.0352x; 1.0036x over previous
; template <int EPI>
; __device__ __forceinline__ void gemm_phase(const GemmDesc d, u16* shm, unsigned sx, unsigned srank, unsigned snloc) {
;     ...
;         const int rl16 = lane2 >> 2, c8 = (lane2 & 3) * 8;
;         f32x4 cs[2][2], cb[2][2];
; #pragma unroll
;         for (int bj = 0; bj < 2; ++bj)
; #pragma unroll
;           for (int hh = 0; hh < 2; ++hh) {
;             const int lcol = bj * 128 + wc2 * 32 + c8 + hh * 4;
;             cs[bj][hh] = f32x4{1.f, 1.f, 1.f, 1.f}; cb[bj][hh] = f32x4{0.f, 0.f, 0.f, 0.f};
;             if constexpr (EPI == E_SEQDFT) { cs[bj][hh] = f32x4{1.f / 1024.f, 1.f / 1024.f, 1.f / 1024.f, 1.f / 1024.f}; cb[bj][hh] = *(const f32x4*)(d.bias + (size_t)z * DM + bcol + lcol); }
;             if constexpr (EPI == E_RESID) {
;               if (d.bias) cb[bj][hh] = *(const f32x4*)(d.bias + bcol + lcol);
;               if (d.scale) cs[bj][hh] = *(const f32x4*)(d.scale + bcol + lcol);
;               cs[bj][hh] = cs[bj][hh] * d.alpha;
;             }
;           }
;         u16* outp = nullptr; int ldo = 0;
;         if constexpr (EPI == E_QKV) { outp = (u16*)((char*)(d.outb + (size_t)brow * DQKV + bcol) + (long)(pm >> 4) * d.o_bskip); ldo = DQKV; }
;         if constexpr (EPI == E_SEQDFT) { outp = d.outb + ((size_t)z * SEQ + brow) * DM + bcol; ldo = DM; }
;         const size_t xbase = (size_t)(brow + wr2 * 64 + rl16) * DM + bcol + wc2 * 32 + c8;
;         u32x4 xi = {0u, 0u, 0u, 0u};
;         if constexpr (EPI == E_RESID) xi = *(const u32x4*)(d.xb + xbase);
; #pragma unroll
;         for (int ai = 0; ai < 2; ++ai)
; #pragma unroll
;           for (int m = 0; m < 4; ++m) {
;             float ps = 0.f;
;             const int lrow = ai * 128 + wr2 * 64 + m * 16 + rl16;
; #pragma unroll
;             for (int bj = 0; bj < 2; ++bj) {
; #pragma unroll
;               for (int n = 0; n < 2; ++n)
; #pragma unroll
;                 for (int j = 0; j < 4; ++j) stg[(fq2 * 4 + j) * 36 + n * 16 + fr2] = acc[ai][bj][m][n][j];
;               u32x4 xc = xi;
;               if constexpr (EPI == E_RESID) {
;                 const int rnd = (ai * 4 + m) * 2 + bj;
;                 if (rnd < 15) {
;                   const int rn = rnd + 1, an = rn >> 3, mn = (rn >> 1) & 3, bn = rn & 1;
;                   xi = *(const u32x4*)(d.xb + xbase + (size_t)(an * 128 + mn * 16) * DM + bn * 128);
;                 }
;               }
.LBB0_1538:
	s_or_b64 exec, exec, s[4:5]
	v_lshrrev_b32_e32 v210, 6, v182
	v_and_b32_e32 v211, 3, v182
	v_bfe_u32 v212, v182, 2, 4
	v_lshrrev_b32_e32 v213, 2, v182
	v_and_b32_e32 v213, 12, v213
	v_and_b32_e32 v148, 15, v182
	v_lshlrev_b32_e32 v148, 2, v148
	v_and_b32_e32 v149, 3, v210
	v_mul_u32_u24_e32 v150, 0x900, v210
	v_add_u32_e32 v150, s83, v150
	v_mul_u32_u24_e32 v152, 0x90, v213
	v_add3_u32 v144, v150, v148, v152
	v_mul_u32_u24_e32 v152, 0x90, v212
	v_lshlrev_b32_e32 v153, 5, v211
	v_add3_u32 v145, v150, v152, v153
	v_lshrrev_b32_e32 v151, 2, v182
	v_and_b32_e32 v151, 0xffffffc0, v151
	v_or_b32_e32 v151, v151, v212
	v_lshlrev_b32_e32 v152, 11, v151
	v_lshlrev_b32_e32 v153, 6, v149
	v_lshlrev_b32_e32 v146, 4, v211
	v_add3_u32 v146, v152, v153, v146
	v_lshlrev_b32_e32 v152, 6, v151
	v_lshlrev_b32_e32 v153, 2, v149
	v_add_u32_e32 v147, v152, v153
	v_cmp_eq_u32_e64 s[10:11], 0, v211
	v_xor_b32_e32 v154, 1, v185
	v_lshlrev_b32_e32 v154, 2, v154
	v_xor_b32_e32 v155, 2, v185
	v_lshlrev_b32_e32 v155, 2, v155
	s_lshl_b32 s0, s88, 19
	s_lshl_b32 s1, s85, 9
	s_add_u32 s0, s0, s1
	s_add_u32 s46, s2, s0
	s_addc_u32 s47, s3, 0
	s_lshl_b32 s0, s88, 14
	s_lshl_b32 s1, s85, 4
	s_add_u32 s0, s0, s1
	s_add_u32 s42, s67, s0
	s_addc_u32 s43, s69, 0
	s_add_u32 s34, s46, 0x0
	s_addc_u32 s35, s47, 0
	global_load_dwordx4 v[158:161], v146, s[34:35]
	global_load_dwordx4 v[162:165], v146, s[34:35] offset:256
	s_add_u32 s34, s46, 0x8000
	s_addc_u32 s35, s47, 0
	global_load_dwordx4 v[166:169], v146, s[34:35]
	global_load_dwordx4 v[170:173], v146, s[34:35] offset:256
	s_add_u32 s34, s46, 0x10000
	s_addc_u32 s35, s47, 0
	global_load_dwordx4 v[178:181], v146, s[34:35]
	global_load_dwordx4 v[190:193], v146, s[34:35] offset:256
	ds_write2_b32 v144, v124, v120 offset1:16
	ds_write2_b32 v144, v125, v121 offset0:36 offset1:52
	ds_write2_b32 v144, v126, v122 offset0:72 offset1:88
	ds_write2_b32 v144, v127, v123 offset0:108 offset1:124
	ds_read_b128 v[194:197], v145
	ds_read_b128 v[198:201], v145 offset:16
	ds_write2_b32 v144, v116, v112 offset1:16
	ds_write2_b32 v144, v117, v113 offset0:36 offset1:52
	ds_write2_b32 v144, v118, v114 offset0:72 offset1:88
	ds_write2_b32 v144, v119, v115 offset0:108 offset1:124
	ds_read_b128 v[202:205], v145
	ds_read_b128 v[206:209], v145 offset:16
	s_waitcnt lgkmcnt(6)
	s_waitcnt vmcnt(5)
	v_lshlrev_b32_e32 v210, 16, v158
	v_and_b32_e32 v211, 0xffff0000, v158
	v_lshlrev_b32_e32 v212, 16, v159
	v_and_b32_e32 v213, 0xffff0000, v159
	v_lshlrev_b32_e32 v148, 16, v160
	v_and_b32_e32 v149, 0xffff0000, v160
	v_lshlrev_b32_e32 v150, 16, v161
	v_and_b32_e32 v151, 0xffff0000, v161
	s_add_u32 s34, s46, 0x18000
	s_addc_u32 s35, s47, 0
	global_load_dwordx4 v[158:161], v146, s[34:35]
	v_pk_fma_f32 v[210:211], v[194:195], 0.5, v[210:211] op_sel_hi:[1,0,1]
	v_pk_fma_f32 v[212:213], v[196:197], 0.5, v[212:213] op_sel_hi:[1,0,1]
	v_pk_fma_f32 v[148:149], v[198:199], 0.5, v[148:149] op_sel_hi:[1,0,1]
	v_pk_fma_f32 v[150:151], v[200:201], 0.5, v[150:151] op_sel_hi:[1,0,1]
	v_cvt_pk_bf16_f32 v194, v210, v211
	v_cvt_pk_bf16_f32 v195, v212, v213
	v_cvt_pk_bf16_f32 v196, v148, v149
	v_cvt_pk_bf16_f32 v197, v150, v151
	s_add_u32 s22, s46, 0x0
	s_addc_u32 s23, s47, 0
	global_store_dwordx4 v146, v[194:197], s[22:23]
	v_pk_mul_f32 v[152:153], v[148:149], v[148:149]
	v_pk_mul_f32 v[156:157], v[150:151], v[150:151]
	v_pk_fma_f32 v[152:153], v[210:211], v[210:211], v[152:153]
	v_pk_fma_f32 v[156:157], v[212:213], v[212:213], v[156:157]
	v_add_f32_e32 v152, v152, v153
	v_add_f32_e32 v153, v156, v157
	v_add_f32_e32 v128, v152, v153
	ds_write2_b32 v144, v108, v104 offset1:16
	ds_write2_b32 v144, v109, v105 offset0:36 offset1:52
	ds_write2_b32 v144, v110, v106 offset0:72 offset1:88
	ds_write2_b32 v144, v111, v107 offset0:108 offset1:124
	ds_read_b128 v[194:197], v145
	ds_read_b128 v[198:201], v145 offset:16
	s_waitcnt lgkmcnt(6)
	s_waitcnt vmcnt(6)
	v_lshlrev_b32_e32 v210, 16, v162
	v_and_b32_e32 v211, 0xffff0000, v162
	v_lshlrev_b32_e32 v212, 16, v163
	v_and_b32_e32 v213, 0xffff0000, v163
	v_lshlrev_b32_e32 v148, 16, v164
	v_and_b32_e32 v149, 0xffff0000, v164
	v_lshlrev_b32_e32 v150, 16, v165
	v_and_b32_e32 v151, 0xffff0000, v165
	global_load_dwordx4 v[162:165], v146, s[34:35] offset:256
	v_pk_fma_f32 v[210:211], v[202:203], 0.5, v[210:211] op_sel_hi:[1,0,1]
	v_pk_fma_f32 v[212:213], v[204:205], 0.5, v[212:213] op_sel_hi:[1,0,1]
	v_pk_fma_f32 v[148:149], v[206:207], 0.5, v[148:149] op_sel_hi:[1,0,1]
	v_pk_fma_f32 v[150:151], v[208:209], 0.5, v[150:151] op_sel_hi:[1,0,1]
	v_cvt_pk_bf16_f32 v202, v210, v211
	v_cvt_pk_bf16_f32 v203, v212, v213
	v_cvt_pk_bf16_f32 v204, v148, v149
	v_cvt_pk_bf16_f32 v205, v150, v151
	global_store_dwordx4 v146, v[202:205], s[22:23] offset:256
	v_pk_mul_f32 v[152:153], v[148:149], v[148:149]
	v_pk_mul_f32 v[156:157], v[150:151], v[150:151]
	v_pk_fma_f32 v[152:153], v[210:211], v[210:211], v[152:153]
	v_pk_fma_f32 v[156:157], v[212:213], v[212:213], v[156:157]
	v_add_f32_e32 v152, v152, v153
	v_add_f32_e32 v153, v156, v157
	v_add_f32_e32 v152, v152, v153
	v_add_f32_e32 v129, v128, v152
	ds_bpermute_b32 v130, v154, v129
	ds_write2_b32 v144, v100, v96 offset1:16
	ds_write2_b32 v144, v101, v97 offset0:36 offset1:52
	ds_write2_b32 v144, v102, v98 offset0:72 offset1:88
	ds_write2_b32 v144, v103, v99 offset0:108 offset1:124
	ds_read_b128 v[202:205], v145
	ds_read_b128 v[206:209], v145 offset:16
	s_waitcnt lgkmcnt(6)
	v_add_f32_e32 v131, v129, v130
	ds_bpermute_b32 v132, v155, v131
	s_waitcnt lgkmcnt(8)
	s_waitcnt vmcnt(7)
; template <int EPI>
; __device__ __forceinline__ void gemm_phase(const GemmDesc d, u16* shm, unsigned sx, unsigned srank, unsigned snloc) {
;     ...
;             for (int bj = 0; bj < 2; ++bj) {
; #pragma unroll
;               for (int n = 0; n < 2; ++n)
; #pragma unroll
;                 for (int j = 0; j < 4; ++j) stg[(fq2 * 4 + j) * 36 + n * 16 + fr2] = acc[ai][bj][m][n][j];
;               u32x4 xc = xi;
;               if constexpr (EPI == E_RESID) {
;                 const int rnd = (ai * 4 + m) * 2 + bj;
;                 if (rnd < 15) {
;                   const int rn = rnd + 1, an = rn >> 3, mn = (rn >> 1) & 3, bn = rn & 1;
;                   xi = *(const u32x4*)(d.xb + xbase + (size_t)(an * 128 + mn * 16) * DM + bn * 128);
;                 }
;               }
;               f32x4 v0 = *(const f32x4*)&stg[rl16 * 36 + c8], v1 = *(const f32x4*)&stg[rl16 * 36 + c8 + 4];
;               if constexpr (EPI == E_RESID) {
;                 const size_t idx = xbase + (size_t)(ai * 128 + m * 16) * DM + bj * 128;
;                 const f32x4 xo0 = {__uint_as_float(xc[0] << 16), __uint_as_float(xc[0] & 0xffff0000u), __uint_as_float(xc[1] << 16), __uint_as_float(xc[1] & 0xffff0000u)};
;                 const f32x4 xo1 = {__uint_as_float(xc[2] << 16), __uint_as_float(xc[2] & 0xffff0000u), __uint_as_float(xc[3] << 16), __uint_as_float(xc[3] & 0xffff0000u)};
;                 const f32x4 xn0 = xo0 + (v0 + cb[bj][0]) * cs[bj][0], xn1 = xo1 + (v1 + cb[bj][1]) * cs[bj][1];
;                 u32x4 w = {pack2(xn0[0], xn0[1]), pack2(xn0[2], xn0[3]), pack2(xn1[0], xn1[1]), pack2(xn1[2], xn1[3])};
;                 *(u32x4*)(d.xb + idx) = w;
;                 const f32x4 sq = xn0 * xn0 + xn1 * xn1;
;                 ps += (sq[0] + sq[1]) + (sq[2] + sq[3]);
;               } else {
;                 if constexpr (EPI == E_QKV) { const float r = lr[lrow]; v0 = v0 * r; v1 = v1 * r; }
;                 else if constexpr (EPI == E_SEQDFT) { const float sg = (rl16 & 1) ? -1.f : 1.f; v0 = (v0 + cb[bj][0] * sg) * cs[bj][0]; v1 = (v1 + cb[bj][1] * sg) * cs[bj][1]; }
;                 else { v0 = v0 * cs[bj][0]; v1 = v1 * cs[bj][1]; }
;                 u32x4 w = {pack2(v0[0], v0[1]), pack2(v0[2], v0[3]), pack2(v1[0], v1[1]), pack2(v1[2], v1[3])};
;                 *(u32x4*)(outp + (size_t)lrow * ldo + bj * 128 + wc2 * 32 + c8) = w;
;               }
;             }
	v_lshlrev_b32_e32 v210, 16, v166
	v_and_b32_e32 v211, 0xffff0000, v166
	v_lshlrev_b32_e32 v212, 16, v167
	v_and_b32_e32 v213, 0xffff0000, v167
	v_lshlrev_b32_e32 v148, 16, v168
	v_and_b32_e32 v149, 0xffff0000, v168
	v_lshlrev_b32_e32 v150, 16, v169
	v_and_b32_e32 v151, 0xffff0000, v169
	s_add_u32 s34, s46, 0x40000
	s_addc_u32 s35, s47, 0
	global_load_dwordx4 v[166:169], v146, s[34:35]
	v_pk_fma_f32 v[210:211], v[194:195], 0.5, v[210:211] op_sel_hi:[1,0,1]
	v_pk_fma_f32 v[212:213], v[196:197], 0.5, v[212:213] op_sel_hi:[1,0,1]
	v_pk_fma_f32 v[148:149], v[198:199], 0.5, v[148:149] op_sel_hi:[1,0,1]
	v_pk_fma_f32 v[150:151], v[200:201], 0.5, v[150:151] op_sel_hi:[1,0,1]
	v_cvt_pk_bf16_f32 v194, v210, v211
	v_cvt_pk_bf16_f32 v195, v212, v213
	v_cvt_pk_bf16_f32 v196, v148, v149
	v_cvt_pk_bf16_f32 v197, v150, v151
	s_add_u32 s22, s46, 0x8000
	s_addc_u32 s23, s47, 0
	global_store_dwordx4 v146, v[194:197], s[22:23]
	v_pk_mul_f32 v[152:153], v[148:149], v[148:149]
	v_pk_mul_f32 v[156:157], v[150:151], v[150:151]
	v_pk_fma_f32 v[152:153], v[210:211], v[210:211], v[152:153]
	v_pk_fma_f32 v[156:157], v[212:213], v[212:213], v[156:157]
	v_add_f32_e32 v152, v152, v153
	v_add_f32_e32 v153, v156, v157
	v_add_f32_e32 v128, v152, v153
	ds_write2_b32 v144, v92, v88 offset1:16
	ds_write2_b32 v144, v93, v89 offset0:36 offset1:52
	ds_write2_b32 v144, v94, v90 offset0:72 offset1:88
	ds_write2_b32 v144, v95, v91 offset0:108 offset1:124
	ds_read_b128 v[194:197], v145
	ds_read_b128 v[198:201], v145 offset:16
	s_waitcnt lgkmcnt(6)
	v_add_f32_e32 v131, v131, v132
	s_add_u32 s94, s42, 0x0
	s_addc_u32 s95, s43, 0
	s_and_saveexec_b64 s[4:5], s[10:11]
	global_store_dword v147, v131, s[94:95]
	s_or_b64 exec, exec, s[4:5]
	s_waitcnt lgkmcnt(7)
	s_waitcnt vmcnt(9)
	v_lshlrev_b32_e32 v210, 16, v170
	v_and_b32_e32 v211, 0xffff0000, v170
	v_lshlrev_b32_e32 v212, 16, v171
	v_and_b32_e32 v213, 0xffff0000, v171
	v_lshlrev_b32_e32 v148, 16, v172
	v_and_b32_e32 v149, 0xffff0000, v172
	v_lshlrev_b32_e32 v150, 16, v173
	v_and_b32_e32 v151, 0xffff0000, v173
	global_load_dwordx4 v[170:173], v146, s[34:35] offset:256
	v_pk_fma_f32 v[210:211], v[202:203], 0.5, v[210:211] op_sel_hi:[1,0,1]
	v_pk_fma_f32 v[212:213], v[204:205], 0.5, v[212:213] op_sel_hi:[1,0,1]
	v_pk_fma_f32 v[148:149], v[206:207], 0.5, v[148:149] op_sel_hi:[1,0,1]
	v_pk_fma_f32 v[150:151], v[208:209], 0.5, v[150:151] op_sel_hi:[1,0,1]
	v_cvt_pk_bf16_f32 v202, v210, v211
	v_cvt_pk_bf16_f32 v203, v212, v213
	v_cvt_pk_bf16_f32 v204, v148, v149
	v_cvt_pk_bf16_f32 v205, v150, v151
	global_store_dwordx4 v146, v[202:205], s[22:23] offset:256
	v_pk_mul_f32 v[152:153], v[148:149], v[148:149]
	v_pk_mul_f32 v[156:157], v[150:151], v[150:151]
	v_pk_fma_f32 v[152:153], v[210:211], v[210:211], v[152:153]
	v_pk_fma_f32 v[156:157], v[212:213], v[212:213], v[156:157]
	v_add_f32_e32 v152, v152, v153
	v_add_f32_e32 v153, v156, v157
	v_add_f32_e32 v152, v152, v153
	v_add_f32_e32 v129, v128, v152
	ds_bpermute_b32 v130, v154, v129
	ds_write2_b32 v144, v84, v80 offset1:16
	ds_write2_b32 v144, v85, v81 offset0:36 offset1:52
	ds_write2_b32 v144, v86, v82 offset0:72 offset1:88
	ds_write2_b32 v144, v87, v83 offset0:108 offset1:124
	ds_read_b128 v[202:205], v145
	ds_read_b128 v[206:209], v145 offset:16
	s_waitcnt lgkmcnt(6)
	v_add_f32_e32 v131, v129, v130
	ds_bpermute_b32 v132, v155, v131
	s_waitcnt lgkmcnt(8)
	s_waitcnt vmcnt(10)
	v_lshlrev_b32_e32 v210, 16, v178
	v_and_b32_e32 v211, 0xffff0000, v178
	v_lshlrev_b32_e32 v212, 16, v179
	v_and_b32_e32 v213, 0xffff0000, v179
	v_lshlrev_b32_e32 v148, 16, v180
	v_and_b32_e32 v149, 0xffff0000, v180
	v_lshlrev_b32_e32 v150, 16, v181
	v_and_b32_e32 v151, 0xffff0000, v181
	s_add_u32 s34, s46, 0x48000
	s_addc_u32 s35, s47, 0
	global_load_dwordx4 v[178:181], v146, s[34:35]
	v_pk_fma_f32 v[210:211], v[194:195], 0.5, v[210:211] op_sel_hi:[1,0,1]
	v_pk_fma_f32 v[212:213], v[196:197], 0.5, v[212:213] op_sel_hi:[1,0,1]
	v_pk_fma_f32 v[148:149], v[198:199], 0.5, v[148:149] op_sel_hi:[1,0,1]
	v_pk_fma_f32 v[150:151], v[200:201], 0.5, v[150:151] op_sel_hi:[1,0,1]
	v_cvt_pk_bf16_f32 v194, v210, v211
	v_cvt_pk_bf16_f32 v195, v212, v213
	v_cvt_pk_bf16_f32 v196, v148, v149
	v_cvt_pk_bf16_f32 v197, v150, v151
	s_add_u32 s22, s46, 0x10000
	s_addc_u32 s23, s47, 0
	global_store_dwordx4 v146, v[194:197], s[22:23]
	v_pk_mul_f32 v[152:153], v[148:149], v[148:149]
	v_pk_mul_f32 v[156:157], v[150:151], v[150:151]
	v_pk_fma_f32 v[152:153], v[210:211], v[210:211], v[152:153]
	v_pk_fma_f32 v[156:157], v[212:213], v[212:213], v[156:157]
	v_add_f32_e32 v152, v152, v153
	v_add_f32_e32 v153, v156, v157
	v_add_f32_e32 v128, v152, v153
	ds_write2_b32 v144, v76, v72 offset1:16
	ds_write2_b32 v144, v77, v73 offset0:36 offset1:52
	ds_write2_b32 v144, v78, v74 offset0:72 offset1:88
	ds_write2_b32 v144, v79, v75 offset0:108 offset1:124
	ds_read_b128 v[194:197], v145
	ds_read_b128 v[198:201], v145 offset:16
	s_waitcnt lgkmcnt(6)
	v_add_f32_e32 v131, v131, v132
	s_add_u32 s94, s42, 0x400
	s_addc_u32 s95, s43, 0
	s_and_saveexec_b64 s[4:5], s[10:11]
	global_store_dword v147, v131, s[94:95]
	s_or_b64 exec, exec, s[4:5]
	s_waitcnt lgkmcnt(7)
	s_waitcnt vmcnt(12)
; template <int EPI>
; __device__ __forceinline__ void gemm_phase(const GemmDesc d, u16* shm, unsigned sx, unsigned srank, unsigned snloc) {
;     ...
;             for (int bj = 0; bj < 2; ++bj) {
; #pragma unroll
;               for (int n = 0; n < 2; ++n)
; #pragma unroll
;                 for (int j = 0; j < 4; ++j) stg[(fq2 * 4 + j) * 36 + n * 16 + fr2] = acc[ai][bj][m][n][j];
;               u32x4 xc = xi;
;               if constexpr (EPI == E_RESID) {
;                 const int rnd = (ai * 4 + m) * 2 + bj;
;                 if (rnd < 15) {
;                   const int rn = rnd + 1, an = rn >> 3, mn = (rn >> 1) & 3, bn = rn & 1;
;                   xi = *(const u32x4*)(d.xb + xbase + (size_t)(an * 128 + mn * 16) * DM + bn * 128);
;                 }
;               }
;               f32x4 v0 = *(const f32x4*)&stg[rl16 * 36 + c8], v1 = *(const f32x4*)&stg[rl16 * 36 + c8 + 4];
;               if constexpr (EPI == E_RESID) {
;                 const size_t idx = xbase + (size_t)(ai * 128 + m * 16) * DM + bj * 128;
;                 const f32x4 xo0 = {__uint_as_float(xc[0] << 16), __uint_as_float(xc[0] & 0xffff0000u), __uint_as_float(xc[1] << 16), __uint_as_float(xc[1] & 0xffff0000u)};
;                 const f32x4 xo1 = {__uint_as_float(xc[2] << 16), __uint_as_float(xc[2] & 0xffff0000u), __uint_as_float(xc[3] << 16), __uint_as_float(xc[3] & 0xffff0000u)};
;                 const f32x4 xn0 = xo0 + (v0 + cb[bj][0]) * cs[bj][0], xn1 = xo1 + (v1 + cb[bj][1]) * cs[bj][1];
;                 u32x4 w = {pack2(xn0[0], xn0[1]), pack2(xn0[2], xn0[3]), pack2(xn1[0], xn1[1]), pack2(xn1[2], xn1[3])};
;                 *(u32x4*)(d.xb + idx) = w;
;                 const f32x4 sq = xn0 * xn0 + xn1 * xn1;
;                 ps += (sq[0] + sq[1]) + (sq[2] + sq[3]);
;               } else {
;                 if constexpr (EPI == E_QKV) { const float r = lr[lrow]; v0 = v0 * r; v1 = v1 * r; }
;                 else if constexpr (EPI == E_SEQDFT) { const float sg = (rl16 & 1) ? -1.f : 1.f; v0 = (v0 + cb[bj][0] * sg) * cs[bj][0]; v1 = (v1 + cb[bj][1] * sg) * cs[bj][1]; }
;                 else { v0 = v0 * cs[bj][0]; v1 = v1 * cs[bj][1]; }
;                 u32x4 w = {pack2(v0[0], v0[1]), pack2(v0[2], v0[3]), pack2(v1[0], v1[1]), pack2(v1[2], v1[3])};
;                 *(u32x4*)(outp + (size_t)lrow * ldo + bj * 128 + wc2 * 32 + c8) = w;
;               }
;             }
	v_lshlrev_b32_e32 v210, 16, v190
	v_and_b32_e32 v211, 0xffff0000, v190
	v_lshlrev_b32_e32 v212, 16, v191
	v_and_b32_e32 v213, 0xffff0000, v191
	v_lshlrev_b32_e32 v148, 16, v192
	v_and_b32_e32 v149, 0xffff0000, v192
	v_lshlrev_b32_e32 v150, 16, v193
	v_and_b32_e32 v151, 0xffff0000, v193
	global_load_dwordx4 v[190:193], v146, s[34:35] offset:256
	v_pk_fma_f32 v[210:211], v[202:203], 0.5, v[210:211] op_sel_hi:[1,0,1]
	v_pk_fma_f32 v[212:213], v[204:205], 0.5, v[212:213] op_sel_hi:[1,0,1]
	v_pk_fma_f32 v[148:149], v[206:207], 0.5, v[148:149] op_sel_hi:[1,0,1]
	v_pk_fma_f32 v[150:151], v[208:209], 0.5, v[150:151] op_sel_hi:[1,0,1]
	v_cvt_pk_bf16_f32 v202, v210, v211
	v_cvt_pk_bf16_f32 v203, v212, v213
	v_cvt_pk_bf16_f32 v204, v148, v149
	v_cvt_pk_bf16_f32 v205, v150, v151
	global_store_dwordx4 v146, v[202:205], s[22:23] offset:256
	v_pk_mul_f32 v[152:153], v[148:149], v[148:149]
	v_pk_mul_f32 v[156:157], v[150:151], v[150:151]
	v_pk_fma_f32 v[152:153], v[210:211], v[210:211], v[152:153]
	v_pk_fma_f32 v[156:157], v[212:213], v[212:213], v[156:157]
	v_add_f32_e32 v152, v152, v153
	v_add_f32_e32 v153, v156, v157
	v_add_f32_e32 v152, v152, v153
	v_add_f32_e32 v129, v128, v152
	ds_bpermute_b32 v130, v154, v129
	ds_write2_b32 v144, v68, v64 offset1:16
	ds_write2_b32 v144, v69, v65 offset0:36 offset1:52
	ds_write2_b32 v144, v70, v66 offset0:72 offset1:88
	ds_write2_b32 v144, v71, v67 offset0:108 offset1:124
	ds_read_b128 v[202:205], v145
	ds_read_b128 v[206:209], v145 offset:16
	s_waitcnt lgkmcnt(6)
	v_add_f32_e32 v131, v129, v130
	ds_bpermute_b32 v132, v155, v131
	s_waitcnt lgkmcnt(8)
	s_waitcnt vmcnt(13)
	v_lshlrev_b32_e32 v210, 16, v158
	v_and_b32_e32 v211, 0xffff0000, v158
	v_lshlrev_b32_e32 v212, 16, v159
	v_and_b32_e32 v213, 0xffff0000, v159
	v_lshlrev_b32_e32 v148, 16, v160
	v_and_b32_e32 v149, 0xffff0000, v160
	v_lshlrev_b32_e32 v150, 16, v161
	v_and_b32_e32 v151, 0xffff0000, v161
	s_add_u32 s34, s46, 0x50000
	s_addc_u32 s35, s47, 0
	global_load_dwordx4 v[158:161], v146, s[34:35]
	v_pk_fma_f32 v[210:211], v[194:195], 0.5, v[210:211] op_sel_hi:[1,0,1]
	v_pk_fma_f32 v[212:213], v[196:197], 0.5, v[212:213] op_sel_hi:[1,0,1]
	v_pk_fma_f32 v[148:149], v[198:199], 0.5, v[148:149] op_sel_hi:[1,0,1]
	v_pk_fma_f32 v[150:151], v[200:201], 0.5, v[150:151] op_sel_hi:[1,0,1]
	v_cvt_pk_bf16_f32 v194, v210, v211
	v_cvt_pk_bf16_f32 v195, v212, v213
	v_cvt_pk_bf16_f32 v196, v148, v149
	v_cvt_pk_bf16_f32 v197, v150, v151
	s_add_u32 s22, s46, 0x18000
	s_addc_u32 s23, s47, 0
	global_store_dwordx4 v146, v[194:197], s[22:23]
	v_pk_mul_f32 v[152:153], v[148:149], v[148:149]
	v_pk_mul_f32 v[156:157], v[150:151], v[150:151]
	v_pk_fma_f32 v[152:153], v[210:211], v[210:211], v[152:153]
	v_pk_fma_f32 v[156:157], v[212:213], v[212:213], v[156:157]
	v_add_f32_e32 v152, v152, v153
	v_add_f32_e32 v153, v156, v157
	v_add_f32_e32 v128, v152, v153
	ds_write2_b32 v144, v60, v56 offset1:16
	ds_write2_b32 v144, v61, v57 offset0:36 offset1:52
	ds_write2_b32 v144, v62, v58 offset0:72 offset1:88
	ds_write2_b32 v144, v63, v59 offset0:108 offset1:124
	ds_read_b128 v[194:197], v145
	ds_read_b128 v[198:201], v145 offset:16
	s_waitcnt lgkmcnt(6)
	v_add_f32_e32 v131, v131, v132
	s_add_u32 s94, s42, 0x800
	s_addc_u32 s95, s43, 0
	s_and_saveexec_b64 s[4:5], s[10:11]
	global_store_dword v147, v131, s[94:95]
	s_or_b64 exec, exec, s[4:5]
	s_waitcnt lgkmcnt(7)
	s_waitcnt vmcnt(14)
	v_lshlrev_b32_e32 v210, 16, v162
	v_and_b32_e32 v211, 0xffff0000, v162
	v_lshlrev_b32_e32 v212, 16, v163
	v_and_b32_e32 v213, 0xffff0000, v163
	v_lshlrev_b32_e32 v148, 16, v164
	v_and_b32_e32 v149, 0xffff0000, v164
	v_lshlrev_b32_e32 v150, 16, v165
	v_and_b32_e32 v151, 0xffff0000, v165
	global_load_dwordx4 v[162:165], v146, s[34:35] offset:256
	v_pk_fma_f32 v[210:211], v[202:203], 0.5, v[210:211] op_sel_hi:[1,0,1]
	v_pk_fma_f32 v[212:213], v[204:205], 0.5, v[212:213] op_sel_hi:[1,0,1]
	v_pk_fma_f32 v[148:149], v[206:207], 0.5, v[148:149] op_sel_hi:[1,0,1]
	v_pk_fma_f32 v[150:151], v[208:209], 0.5, v[150:151] op_sel_hi:[1,0,1]
	v_cvt_pk_bf16_f32 v202, v210, v211
	v_cvt_pk_bf16_f32 v203, v212, v213
	v_cvt_pk_bf16_f32 v204, v148, v149
	v_cvt_pk_bf16_f32 v205, v150, v151
	global_store_dwordx4 v146, v[202:205], s[22:23] offset:256
	v_pk_mul_f32 v[152:153], v[148:149], v[148:149]
	v_pk_mul_f32 v[156:157], v[150:151], v[150:151]
	v_pk_fma_f32 v[152:153], v[210:211], v[210:211], v[152:153]
	v_pk_fma_f32 v[156:157], v[212:213], v[212:213], v[156:157]
	v_add_f32_e32 v152, v152, v153
	v_add_f32_e32 v153, v156, v157
	v_add_f32_e32 v152, v152, v153
	v_add_f32_e32 v129, v128, v152
	ds_bpermute_b32 v130, v154, v129
	ds_write2_b32 v144, v52, v48 offset1:16
	ds_write2_b32 v144, v53, v49 offset0:36 offset1:52
	ds_write2_b32 v144, v54, v50 offset0:72 offset1:88
	ds_write2_b32 v144, v55, v51 offset0:108 offset1:124
	ds_read_b128 v[202:205], v145
	ds_read_b128 v[206:209], v145 offset:16
	s_waitcnt lgkmcnt(6)
	v_add_f32_e32 v131, v129, v130
	ds_bpermute_b32 v132, v155, v131
	s_waitcnt lgkmcnt(8)
	s_waitcnt vmcnt(14)
; template <int EPI>
; __device__ __forceinline__ void gemm_phase(const GemmDesc d, u16* shm, unsigned sx, unsigned srank, unsigned snloc) {
;     ...
;             for (int bj = 0; bj < 2; ++bj) {
; #pragma unroll
;               for (int n = 0; n < 2; ++n)
; #pragma unroll
;                 for (int j = 0; j < 4; ++j) stg[(fq2 * 4 + j) * 36 + n * 16 + fr2] = acc[ai][bj][m][n][j];
;               u32x4 xc = xi;
;               if constexpr (EPI == E_RESID) {
;                 const int rnd = (ai * 4 + m) * 2 + bj;
;                 if (rnd < 15) {
;                   const int rn = rnd + 1, an = rn >> 3, mn = (rn >> 1) & 3, bn = rn & 1;
;                   xi = *(const u32x4*)(d.xb + xbase + (size_t)(an * 128 + mn * 16) * DM + bn * 128);
;                 }
;               }
;               f32x4 v0 = *(const f32x4*)&stg[rl16 * 36 + c8], v1 = *(const f32x4*)&stg[rl16 * 36 + c8 + 4];
;               if constexpr (EPI == E_RESID) {
;                 const size_t idx = xbase + (size_t)(ai * 128 + m * 16) * DM + bj * 128;
;                 const f32x4 xo0 = {__uint_as_float(xc[0] << 16), __uint_as_float(xc[0] & 0xffff0000u), __uint_as_float(xc[1] << 16), __uint_as_float(xc[1] & 0xffff0000u)};
;                 const f32x4 xo1 = {__uint_as_float(xc[2] << 16), __uint_as_float(xc[2] & 0xffff0000u), __uint_as_float(xc[3] << 16), __uint_as_float(xc[3] & 0xffff0000u)};
;                 const f32x4 xn0 = xo0 + (v0 + cb[bj][0]) * cs[bj][0], xn1 = xo1 + (v1 + cb[bj][1]) * cs[bj][1];
;                 u32x4 w = {pack2(xn0[0], xn0[1]), pack2(xn0[2], xn0[3]), pack2(xn1[0], xn1[1]), pack2(xn1[2], xn1[3])};
;                 *(u32x4*)(d.xb + idx) = w;
;                 const f32x4 sq = xn0 * xn0 + xn1 * xn1;
;                 ps += (sq[0] + sq[1]) + (sq[2] + sq[3]);
;               } else {
;                 if constexpr (EPI == E_QKV) { const float r = lr[lrow]; v0 = v0 * r; v1 = v1 * r; }
;                 else if constexpr (EPI == E_SEQDFT) { const float sg = (rl16 & 1) ? -1.f : 1.f; v0 = (v0 + cb[bj][0] * sg) * cs[bj][0]; v1 = (v1 + cb[bj][1] * sg) * cs[bj][1]; }
;                 else { v0 = v0 * cs[bj][0]; v1 = v1 * cs[bj][1]; }
;                 u32x4 w = {pack2(v0[0], v0[1]), pack2(v0[2], v0[3]), pack2(v1[0], v1[1]), pack2(v1[2], v1[3])};
;                 *(u32x4*)(outp + (size_t)lrow * ldo + bj * 128 + wc2 * 32 + c8) = w;
;               }
;             }
	v_lshlrev_b32_e32 v210, 16, v166
	v_and_b32_e32 v211, 0xffff0000, v166
	v_lshlrev_b32_e32 v212, 16, v167
	v_and_b32_e32 v213, 0xffff0000, v167
	v_lshlrev_b32_e32 v148, 16, v168
	v_and_b32_e32 v149, 0xffff0000, v168
	v_lshlrev_b32_e32 v150, 16, v169
	v_and_b32_e32 v151, 0xffff0000, v169
	s_add_u32 s34, s46, 0x58000
	s_addc_u32 s35, s47, 0
	global_load_dwordx4 v[166:169], v146, s[34:35]
	v_pk_fma_f32 v[210:211], v[194:195], 0.5, v[210:211] op_sel_hi:[1,0,1]
	v_pk_fma_f32 v[212:213], v[196:197], 0.5, v[212:213] op_sel_hi:[1,0,1]
	v_pk_fma_f32 v[148:149], v[198:199], 0.5, v[148:149] op_sel_hi:[1,0,1]
	v_pk_fma_f32 v[150:151], v[200:201], 0.5, v[150:151] op_sel_hi:[1,0,1]
	v_cvt_pk_bf16_f32 v194, v210, v211
	v_cvt_pk_bf16_f32 v195, v212, v213
	v_cvt_pk_bf16_f32 v196, v148, v149
	v_cvt_pk_bf16_f32 v197, v150, v151
	s_add_u32 s22, s46, 0x40000
	s_addc_u32 s23, s47, 0
	global_store_dwordx4 v146, v[194:197], s[22:23]
	v_pk_mul_f32 v[152:153], v[148:149], v[148:149]
	v_pk_mul_f32 v[156:157], v[150:151], v[150:151]
	v_pk_fma_f32 v[152:153], v[210:211], v[210:211], v[152:153]
	v_pk_fma_f32 v[156:157], v[212:213], v[212:213], v[156:157]
	v_add_f32_e32 v152, v152, v153
	v_add_f32_e32 v153, v156, v157
	v_add_f32_e32 v128, v152, v153
	ds_write2_b32 v144, v44, v40 offset1:16
	ds_write2_b32 v144, v45, v41 offset0:36 offset1:52
	ds_write2_b32 v144, v46, v42 offset0:72 offset1:88
	ds_write2_b32 v144, v47, v43 offset0:108 offset1:124
	ds_read_b128 v[194:197], v145
	ds_read_b128 v[198:201], v145 offset:16
	s_waitcnt lgkmcnt(6)
	v_add_f32_e32 v131, v131, v132
	s_add_u32 s94, s42, 0xc00
	s_addc_u32 s95, s43, 0
	s_and_saveexec_b64 s[4:5], s[10:11]
	global_store_dword v147, v131, s[94:95]
	s_or_b64 exec, exec, s[4:5]
	s_waitcnt lgkmcnt(7)
	s_waitcnt vmcnt(14)
	v_lshlrev_b32_e32 v210, 16, v170
	v_and_b32_e32 v211, 0xffff0000, v170
	v_lshlrev_b32_e32 v212, 16, v171
	v_and_b32_e32 v213, 0xffff0000, v171
	v_lshlrev_b32_e32 v148, 16, v172
	v_and_b32_e32 v149, 0xffff0000, v172
	v_lshlrev_b32_e32 v150, 16, v173
	v_and_b32_e32 v151, 0xffff0000, v173
	global_load_dwordx4 v[170:173], v146, s[34:35] offset:256
	v_pk_fma_f32 v[210:211], v[202:203], 0.5, v[210:211] op_sel_hi:[1,0,1]
	v_pk_fma_f32 v[212:213], v[204:205], 0.5, v[212:213] op_sel_hi:[1,0,1]
	v_pk_fma_f32 v[148:149], v[206:207], 0.5, v[148:149] op_sel_hi:[1,0,1]
	v_pk_fma_f32 v[150:151], v[208:209], 0.5, v[150:151] op_sel_hi:[1,0,1]
	v_cvt_pk_bf16_f32 v202, v210, v211
	v_cvt_pk_bf16_f32 v203, v212, v213
	v_cvt_pk_bf16_f32 v204, v148, v149
	v_cvt_pk_bf16_f32 v205, v150, v151
	global_store_dwordx4 v146, v[202:205], s[22:23] offset:256
	v_pk_mul_f32 v[152:153], v[148:149], v[148:149]
	v_pk_mul_f32 v[156:157], v[150:151], v[150:151]
	v_pk_fma_f32 v[152:153], v[210:211], v[210:211], v[152:153]
	v_pk_fma_f32 v[156:157], v[212:213], v[212:213], v[156:157]
	v_add_f32_e32 v152, v152, v153
	v_add_f32_e32 v153, v156, v157
	v_add_f32_e32 v152, v152, v153
	v_add_f32_e32 v129, v128, v152
	ds_bpermute_b32 v130, v154, v129
	ds_write2_b32 v144, v36, v32 offset1:16
	ds_write2_b32 v144, v37, v33 offset0:36 offset1:52
	ds_write2_b32 v144, v38, v34 offset0:72 offset1:88
	ds_write2_b32 v144, v39, v35 offset0:108 offset1:124
	ds_read_b128 v[202:205], v145
	ds_read_b128 v[206:209], v145 offset:16
	s_waitcnt lgkmcnt(6)
	v_add_f32_e32 v131, v129, v130
	ds_bpermute_b32 v132, v155, v131
	s_waitcnt lgkmcnt(8)
	s_waitcnt vmcnt(14)
	v_lshlrev_b32_e32 v210, 16, v178
	v_and_b32_e32 v211, 0xffff0000, v178
	v_lshlrev_b32_e32 v212, 16, v179
	v_and_b32_e32 v213, 0xffff0000, v179
	v_lshlrev_b32_e32 v148, 16, v180
	v_and_b32_e32 v149, 0xffff0000, v180
	v_lshlrev_b32_e32 v150, 16, v181
	v_and_b32_e32 v151, 0xffff0000, v181
	v_pk_fma_f32 v[210:211], v[194:195], 0.5, v[210:211] op_sel_hi:[1,0,1]
	v_pk_fma_f32 v[212:213], v[196:197], 0.5, v[212:213] op_sel_hi:[1,0,1]
	v_pk_fma_f32 v[148:149], v[198:199], 0.5, v[148:149] op_sel_hi:[1,0,1]
	v_pk_fma_f32 v[150:151], v[200:201], 0.5, v[150:151] op_sel_hi:[1,0,1]
	v_cvt_pk_bf16_f32 v194, v210, v211
	v_cvt_pk_bf16_f32 v195, v212, v213
	v_cvt_pk_bf16_f32 v196, v148, v149
	v_cvt_pk_bf16_f32 v197, v150, v151
	s_add_u32 s22, s46, 0x48000
	s_addc_u32 s23, s47, 0
	global_store_dwordx4 v146, v[194:197], s[22:23]
	v_pk_mul_f32 v[152:153], v[148:149], v[148:149]
	v_pk_mul_f32 v[156:157], v[150:151], v[150:151]
	v_pk_fma_f32 v[152:153], v[210:211], v[210:211], v[152:153]
	v_pk_fma_f32 v[156:157], v[212:213], v[212:213], v[156:157]
	v_add_f32_e32 v152, v152, v153
	v_add_f32_e32 v153, v156, v157
	v_add_f32_e32 v128, v152, v153
	ds_write2_b32 v144, v28, v24 offset1:16
	ds_write2_b32 v144, v29, v25 offset0:36 offset1:52
	ds_write2_b32 v144, v30, v26 offset0:72 offset1:88
	ds_write2_b32 v144, v31, v27 offset0:108 offset1:124
	ds_read_b128 v[194:197], v145
	ds_read_b128 v[198:201], v145 offset:16
	s_waitcnt lgkmcnt(6)
	v_add_f32_e32 v131, v131, v132
	s_add_u32 s94, s42, 0x2000
	s_addc_u32 s95, s43, 0
	s_and_saveexec_b64 s[4:5], s[10:11]
	global_store_dword v147, v131, s[94:95]
	s_or_b64 exec, exec, s[4:5]
	s_waitcnt lgkmcnt(7)
	s_waitcnt vmcnt(13)
; template <int EPI>
; __device__ __forceinline__ void gemm_phase(const GemmDesc d, u16* shm, unsigned sx, unsigned srank, unsigned snloc) {
;     ...
;             for (int bj = 0; bj < 2; ++bj) {
; #pragma unroll
;               for (int n = 0; n < 2; ++n)
; #pragma unroll
;                 for (int j = 0; j < 4; ++j) stg[(fq2 * 4 + j) * 36 + n * 16 + fr2] = acc[ai][bj][m][n][j];
;               u32x4 xc = xi;
;               if constexpr (EPI == E_RESID) {
;                 const int rnd = (ai * 4 + m) * 2 + bj;
;                 if (rnd < 15) {
;                   const int rn = rnd + 1, an = rn >> 3, mn = (rn >> 1) & 3, bn = rn & 1;
;                   xi = *(const u32x4*)(d.xb + xbase + (size_t)(an * 128 + mn * 16) * DM + bn * 128);
;                 }
;               }
;               f32x4 v0 = *(const f32x4*)&stg[rl16 * 36 + c8], v1 = *(const f32x4*)&stg[rl16 * 36 + c8 + 4];
;               if constexpr (EPI == E_RESID) {
;                 const size_t idx = xbase + (size_t)(ai * 128 + m * 16) * DM + bj * 128;
;                 const f32x4 xo0 = {__uint_as_float(xc[0] << 16), __uint_as_float(xc[0] & 0xffff0000u), __uint_as_float(xc[1] << 16), __uint_as_float(xc[1] & 0xffff0000u)};
;                 const f32x4 xo1 = {__uint_as_float(xc[2] << 16), __uint_as_float(xc[2] & 0xffff0000u), __uint_as_float(xc[3] << 16), __uint_as_float(xc[3] & 0xffff0000u)};
;                 const f32x4 xn0 = xo0 + (v0 + cb[bj][0]) * cs[bj][0], xn1 = xo1 + (v1 + cb[bj][1]) * cs[bj][1];
;                 u32x4 w = {pack2(xn0[0], xn0[1]), pack2(xn0[2], xn0[3]), pack2(xn1[0], xn1[1]), pack2(xn1[2], xn1[3])};
;                 *(u32x4*)(d.xb + idx) = w;
;                 const f32x4 sq = xn0 * xn0 + xn1 * xn1;
;                 ps += (sq[0] + sq[1]) + (sq[2] + sq[3]);
;               } else {
;                 if constexpr (EPI == E_QKV) { const float r = lr[lrow]; v0 = v0 * r; v1 = v1 * r; }
;                 else if constexpr (EPI == E_SEQDFT) { const float sg = (rl16 & 1) ? -1.f : 1.f; v0 = (v0 + cb[bj][0] * sg) * cs[bj][0]; v1 = (v1 + cb[bj][1] * sg) * cs[bj][1]; }
;                 else { v0 = v0 * cs[bj][0]; v1 = v1 * cs[bj][1]; }
;                 u32x4 w = {pack2(v0[0], v0[1]), pack2(v0[2], v0[3]), pack2(v1[0], v1[1]), pack2(v1[2], v1[3])};
;                 *(u32x4*)(outp + (size_t)lrow * ldo + bj * 128 + wc2 * 32 + c8) = w;
;               }
;             }
	v_lshlrev_b32_e32 v210, 16, v190
	v_and_b32_e32 v211, 0xffff0000, v190
	v_lshlrev_b32_e32 v212, 16, v191
	v_and_b32_e32 v213, 0xffff0000, v191
	v_lshlrev_b32_e32 v148, 16, v192
	v_and_b32_e32 v149, 0xffff0000, v192
	v_lshlrev_b32_e32 v150, 16, v193
	v_and_b32_e32 v151, 0xffff0000, v193
	v_pk_fma_f32 v[210:211], v[202:203], 0.5, v[210:211] op_sel_hi:[1,0,1]
	v_pk_fma_f32 v[212:213], v[204:205], 0.5, v[212:213] op_sel_hi:[1,0,1]
	v_pk_fma_f32 v[148:149], v[206:207], 0.5, v[148:149] op_sel_hi:[1,0,1]
	v_pk_fma_f32 v[150:151], v[208:209], 0.5, v[150:151] op_sel_hi:[1,0,1]
	v_cvt_pk_bf16_f32 v202, v210, v211
	v_cvt_pk_bf16_f32 v203, v212, v213
	v_cvt_pk_bf16_f32 v204, v148, v149
	v_cvt_pk_bf16_f32 v205, v150, v151
	global_store_dwordx4 v146, v[202:205], s[22:23] offset:256
	v_pk_mul_f32 v[152:153], v[148:149], v[148:149]
	v_pk_mul_f32 v[156:157], v[150:151], v[150:151]
	v_pk_fma_f32 v[152:153], v[210:211], v[210:211], v[152:153]
	v_pk_fma_f32 v[156:157], v[212:213], v[212:213], v[156:157]
	v_add_f32_e32 v152, v152, v153
	v_add_f32_e32 v153, v156, v157
	v_add_f32_e32 v152, v152, v153
	v_add_f32_e32 v129, v128, v152
	ds_bpermute_b32 v130, v154, v129
	ds_write2_b32 v144, v20, v16 offset1:16
	ds_write2_b32 v144, v21, v17 offset0:36 offset1:52
	ds_write2_b32 v144, v22, v18 offset0:72 offset1:88
	ds_write2_b32 v144, v23, v19 offset0:108 offset1:124
	ds_read_b128 v[202:205], v145
	ds_read_b128 v[206:209], v145 offset:16
	s_waitcnt lgkmcnt(6)
	v_add_f32_e32 v131, v129, v130
	ds_bpermute_b32 v132, v155, v131
	s_waitcnt lgkmcnt(8)
	s_waitcnt vmcnt(12)
	v_lshlrev_b32_e32 v210, 16, v158
	v_and_b32_e32 v211, 0xffff0000, v158
	v_lshlrev_b32_e32 v212, 16, v159
	v_and_b32_e32 v213, 0xffff0000, v159
	v_lshlrev_b32_e32 v148, 16, v160
	v_and_b32_e32 v149, 0xffff0000, v160
	v_lshlrev_b32_e32 v150, 16, v161
	v_and_b32_e32 v151, 0xffff0000, v161
	v_pk_fma_f32 v[210:211], v[194:195], 0.5, v[210:211] op_sel_hi:[1,0,1]
	v_pk_fma_f32 v[212:213], v[196:197], 0.5, v[212:213] op_sel_hi:[1,0,1]
	v_pk_fma_f32 v[148:149], v[198:199], 0.5, v[148:149] op_sel_hi:[1,0,1]
	v_pk_fma_f32 v[150:151], v[200:201], 0.5, v[150:151] op_sel_hi:[1,0,1]
	v_cvt_pk_bf16_f32 v194, v210, v211
	v_cvt_pk_bf16_f32 v195, v212, v213
	v_cvt_pk_bf16_f32 v196, v148, v149
	v_cvt_pk_bf16_f32 v197, v150, v151
	s_add_u32 s22, s46, 0x50000
	s_addc_u32 s23, s47, 0
	global_store_dwordx4 v146, v[194:197], s[22:23]
	v_pk_mul_f32 v[152:153], v[148:149], v[148:149]
	v_pk_mul_f32 v[156:157], v[150:151], v[150:151]
	v_pk_fma_f32 v[152:153], v[210:211], v[210:211], v[152:153]
	v_pk_fma_f32 v[156:157], v[212:213], v[212:213], v[156:157]
	v_add_f32_e32 v152, v152, v153
	v_add_f32_e32 v153, v156, v157
	v_add_f32_e32 v128, v152, v153
	ds_write2_b32 v144, v12, v8 offset1:16
	ds_write2_b32 v144, v13, v9 offset0:36 offset1:52
	ds_write2_b32 v144, v14, v10 offset0:72 offset1:88
	ds_write2_b32 v144, v15, v11 offset0:108 offset1:124
	ds_read_b128 v[194:197], v145
	ds_read_b128 v[198:201], v145 offset:16
	s_waitcnt lgkmcnt(6)
	v_add_f32_e32 v131, v131, v132
	s_add_u32 s94, s42, 0x2400
	s_addc_u32 s95, s43, 0
	s_and_saveexec_b64 s[4:5], s[10:11]
	global_store_dword v147, v131, s[94:95]
	s_or_b64 exec, exec, s[4:5]
	s_waitcnt lgkmcnt(7)
	s_waitcnt vmcnt(11)
; template <int EPI>
; __device__ __forceinline__ void gemm_phase(const GemmDesc d, u16* shm, unsigned sx, unsigned srank, unsigned snloc) {
;     ...
;             for (int bj = 0; bj < 2; ++bj) {
; #pragma unroll
;               for (int n = 0; n < 2; ++n)
; #pragma unroll
;                 for (int j = 0; j < 4; ++j) stg[(fq2 * 4 + j) * 36 + n * 16 + fr2] = acc[ai][bj][m][n][j];
;               u32x4 xc = xi;
;               if constexpr (EPI == E_RESID) {
;                 const int rnd = (ai * 4 + m) * 2 + bj;
;                 if (rnd < 15) {
;                   const int rn = rnd + 1, an = rn >> 3, mn = (rn >> 1) & 3, bn = rn & 1;
;                   xi = *(const u32x4*)(d.xb + xbase + (size_t)(an * 128 + mn * 16) * DM + bn * 128);
;                 }
;               }
;               f32x4 v0 = *(const f32x4*)&stg[rl16 * 36 + c8], v1 = *(const f32x4*)&stg[rl16 * 36 + c8 + 4];
;               if constexpr (EPI == E_RESID) {
;                 const size_t idx = xbase + (size_t)(ai * 128 + m * 16) * DM + bj * 128;
;                 const f32x4 xo0 = {__uint_as_float(xc[0] << 16), __uint_as_float(xc[0] & 0xffff0000u), __uint_as_float(xc[1] << 16), __uint_as_float(xc[1] & 0xffff0000u)};
;                 const f32x4 xo1 = {__uint_as_float(xc[2] << 16), __uint_as_float(xc[2] & 0xffff0000u), __uint_as_float(xc[3] << 16), __uint_as_float(xc[3] & 0xffff0000u)};
;                 const f32x4 xn0 = xo0 + (v0 + cb[bj][0]) * cs[bj][0], xn1 = xo1 + (v1 + cb[bj][1]) * cs[bj][1];
;                 u32x4 w = {pack2(xn0[0], xn0[1]), pack2(xn0[2], xn0[3]), pack2(xn1[0], xn1[1]), pack2(xn1[2], xn1[3])};
;                 *(u32x4*)(d.xb + idx) = w;
;                 const f32x4 sq = xn0 * xn0 + xn1 * xn1;
;                 ps += (sq[0] + sq[1]) + (sq[2] + sq[3]);
;               } else {
;                 if constexpr (EPI == E_QKV) { const float r = lr[lrow]; v0 = v0 * r; v1 = v1 * r; }
;                 else if constexpr (EPI == E_SEQDFT) { const float sg = (rl16 & 1) ? -1.f : 1.f; v0 = (v0 + cb[bj][0] * sg) * cs[bj][0]; v1 = (v1 + cb[bj][1] * sg) * cs[bj][1]; }
;                 else { v0 = v0 * cs[bj][0]; v1 = v1 * cs[bj][1]; }
;                 u32x4 w = {pack2(v0[0], v0[1]), pack2(v0[2], v0[3]), pack2(v1[0], v1[1]), pack2(v1[2], v1[3])};
;                 *(u32x4*)(outp + (size_t)lrow * ldo + bj * 128 + wc2 * 32 + c8) = w;
;               }
;             }
	v_lshlrev_b32_e32 v210, 16, v162
	v_and_b32_e32 v211, 0xffff0000, v162
	v_lshlrev_b32_e32 v212, 16, v163
	v_and_b32_e32 v213, 0xffff0000, v163
	v_lshlrev_b32_e32 v148, 16, v164
	v_and_b32_e32 v149, 0xffff0000, v164
	v_lshlrev_b32_e32 v150, 16, v165
	v_and_b32_e32 v151, 0xffff0000, v165
	v_pk_fma_f32 v[210:211], v[202:203], 0.5, v[210:211] op_sel_hi:[1,0,1]
	v_pk_fma_f32 v[212:213], v[204:205], 0.5, v[212:213] op_sel_hi:[1,0,1]
	v_pk_fma_f32 v[148:149], v[206:207], 0.5, v[148:149] op_sel_hi:[1,0,1]
	v_pk_fma_f32 v[150:151], v[208:209], 0.5, v[150:151] op_sel_hi:[1,0,1]
	v_cvt_pk_bf16_f32 v202, v210, v211
	v_cvt_pk_bf16_f32 v203, v212, v213
	v_cvt_pk_bf16_f32 v204, v148, v149
	v_cvt_pk_bf16_f32 v205, v150, v151
	global_store_dwordx4 v146, v[202:205], s[22:23] offset:256
	v_pk_mul_f32 v[152:153], v[148:149], v[148:149]
	v_pk_mul_f32 v[156:157], v[150:151], v[150:151]
	v_pk_fma_f32 v[152:153], v[210:211], v[210:211], v[152:153]
	v_pk_fma_f32 v[156:157], v[212:213], v[212:213], v[156:157]
	v_add_f32_e32 v152, v152, v153
	v_add_f32_e32 v153, v156, v157
	v_add_f32_e32 v152, v152, v153
	v_add_f32_e32 v129, v128, v152
	ds_bpermute_b32 v130, v154, v129
	ds_write2_b32 v144, v4, v0 offset1:16
	ds_write2_b32 v144, v5, v1 offset0:36 offset1:52
	ds_write2_b32 v144, v6, v2 offset0:72 offset1:88
	ds_write2_b32 v144, v7, v3 offset0:108 offset1:124
	ds_read_b128 v[202:205], v145
	ds_read_b128 v[206:209], v145 offset:16
	s_waitcnt lgkmcnt(6)
	v_add_f32_e32 v131, v129, v130
	ds_bpermute_b32 v132, v155, v131
	s_waitcnt lgkmcnt(8)
	s_waitcnt vmcnt(10)
	v_lshlrev_b32_e32 v210, 16, v166
	v_and_b32_e32 v211, 0xffff0000, v166
	v_lshlrev_b32_e32 v212, 16, v167
	v_and_b32_e32 v213, 0xffff0000, v167
	v_lshlrev_b32_e32 v148, 16, v168
	v_and_b32_e32 v149, 0xffff0000, v168
	v_lshlrev_b32_e32 v150, 16, v169
	v_and_b32_e32 v151, 0xffff0000, v169
	v_pk_fma_f32 v[210:211], v[194:195], 0.5, v[210:211] op_sel_hi:[1,0,1]
	v_pk_fma_f32 v[212:213], v[196:197], 0.5, v[212:213] op_sel_hi:[1,0,1]
	v_pk_fma_f32 v[148:149], v[198:199], 0.5, v[148:149] op_sel_hi:[1,0,1]
	v_pk_fma_f32 v[150:151], v[200:201], 0.5, v[150:151] op_sel_hi:[1,0,1]
	v_cvt_pk_bf16_f32 v194, v210, v211
	v_cvt_pk_bf16_f32 v195, v212, v213
	v_cvt_pk_bf16_f32 v196, v148, v149
	v_cvt_pk_bf16_f32 v197, v150, v151
	s_add_u32 s22, s46, 0x58000
	s_addc_u32 s23, s47, 0
	global_store_dwordx4 v146, v[194:197], s[22:23]
	v_pk_mul_f32 v[152:153], v[148:149], v[148:149]
	v_pk_mul_f32 v[156:157], v[150:151], v[150:151]
	v_pk_fma_f32 v[152:153], v[210:211], v[210:211], v[152:153]
	v_pk_fma_f32 v[156:157], v[212:213], v[212:213], v[156:157]
	v_add_f32_e32 v152, v152, v153
	v_add_f32_e32 v153, v156, v157
	v_add_f32_e32 v128, v152, v153
	s_waitcnt lgkmcnt(0)
	v_add_f32_e32 v131, v131, v132
	s_add_u32 s94, s42, 0x2800
	s_addc_u32 s95, s43, 0
	s_and_saveexec_b64 s[4:5], s[10:11]
	global_store_dword v147, v131, s[94:95]
	s_or_b64 exec, exec, s[4:5]
	s_waitcnt lgkmcnt(1)
	s_waitcnt vmcnt(9)
	v_lshlrev_b32_e32 v210, 16, v170
	v_and_b32_e32 v211, 0xffff0000, v170
	v_lshlrev_b32_e32 v212, 16, v171
	v_and_b32_e32 v213, 0xffff0000, v171
	v_lshlrev_b32_e32 v148, 16, v172
	v_and_b32_e32 v149, 0xffff0000, v172
	v_lshlrev_b32_e32 v150, 16, v173
	v_and_b32_e32 v151, 0xffff0000, v173
	v_pk_fma_f32 v[210:211], v[202:203], 0.5, v[210:211] op_sel_hi:[1,0,1]
	v_pk_fma_f32 v[212:213], v[204:205], 0.5, v[212:213] op_sel_hi:[1,0,1]
	v_pk_fma_f32 v[148:149], v[206:207], 0.5, v[148:149] op_sel_hi:[1,0,1]
	v_pk_fma_f32 v[150:151], v[208:209], 0.5, v[150:151] op_sel_hi:[1,0,1]
	v_cvt_pk_bf16_f32 v202, v210, v211
	v_cvt_pk_bf16_f32 v203, v212, v213
	v_cvt_pk_bf16_f32 v204, v148, v149
	v_cvt_pk_bf16_f32 v205, v150, v151
	global_store_dwordx4 v146, v[202:205], s[22:23] offset:256
	v_pk_mul_f32 v[152:153], v[148:149], v[148:149]
	v_pk_mul_f32 v[156:157], v[150:151], v[150:151]
	v_pk_fma_f32 v[152:153], v[210:211], v[210:211], v[152:153]
	v_pk_fma_f32 v[156:157], v[212:213], v[212:213], v[156:157]
	v_add_f32_e32 v152, v152, v153
	v_add_f32_e32 v153, v156, v157
	v_add_f32_e32 v152, v152, v153
	v_add_f32_e32 v129, v128, v152
	ds_bpermute_b32 v130, v154, v129
	s_waitcnt lgkmcnt(0)
	v_add_f32_e32 v131, v129, v130
	ds_bpermute_b32 v132, v155, v131
	s_waitcnt lgkmcnt(0)
	v_add_f32_e32 v131, v131, v132
	s_add_u32 s94, s42, 0x2c00
	s_addc_u32 s95, s43, 0
	s_and_saveexec_b64 s[4:5], s[10:11]
	global_store_dword v147, v131, s[94:95]
	s_or_b64 exec, exec, s[4:5]
	s_mov_b32 s31, 0x800000
	s_movk_i32 s28, 0x1000
	s_mov_b64 s[4:5], 0
